# GEMM K-loop: mid-section priority flip pairs and the redundant post-barrier LDS wait removed
# speedup vs baseline: 1.0026x; 1.0026x over previous
; #define PG8_STAGE(bufoff, gbase, voff) do { _Pragma("unroll") for (int _i = 0; _i < 2; ++_i) \
;         __builtin_amdgcn_global_load_lds((const unsigned*)((const char*)(gbase) + (voff)[_i]), (LAS unsigned*)(lds + (bufoff) + ldsw + _i * 8192), 16, 0, 0); } while (0)
; #define PG8_LDA(dst, b, h) do { _Pragma("unroll") for (int m = 0; m < 4; ++m) _Pragma("unroll") for (int k = 0; k < 2; ++k) dst[m][k] = *(const LAS bf16x8*)(lds + PG8_SA(b, h) + aoff + m * 2048 + k * 1024); } while (0)
; #define PG8_LDB(dst, b, h) do { _Pragma("unroll") for (int n = 0; n < 2; ++n) _Pragma("unroll") for (int k = 0; k < 2; ++k) dst[n][k] = *(const LAS bf16x8*)(lds + PG8_SB(b, h) + boff + n * 2048 + k * 1024); } while (0)
; #define PG8_MMA(ai, bj, At, Bt) do { __builtin_amdgcn_s_setprio(1); _Pragma("unroll") for (int m = 0; m < 4; ++m) _Pragma("unroll") for (int n = 0; n < 2; ++n) _Pragma("unroll") for (int k = 0; k < 2; ++k) \
;         acc[ai][bj][m][n] = __builtin_amdgcn_mfma_f32_16x16x32_bf16(Bt[n][k], At[m][k], acc[ai][bj][m][n], 0, 0, 0); __builtin_amdgcn_s_setprio(0); } while (0)
; #define PG8_WAIT_V(n) asm volatile("s_waitcnt vmcnt(" #n ")" ::: "memory")
; #define PG8_WAIT_L(n) asm volatile("s_waitcnt lgkmcnt(" #n ")" ::: "memory")
; #define PG8_BAR __builtin_amdgcn_s_barrier()
; #define PG8_SCHED __builtin_amdgcn_sched_barrier(0)
; template <class Epi>
; DI void gemm_phase(LAS unsigned char* lds, const Gemm g, const StaticOrder& S, const Epi& E) {
;     ...
;             PG8_LDB(B0, 0, 0); PG8_LDB(B1, 0, 1); PG8_SCHED; PG8_LDA(At, 0, 0); PG8_STAGE(PG8_SA(1, 1), a1 + hstepA, voffA);
;             PG8_WAIT_V(8); PG8_WAIT_L(0); PG8_BAR; PG8_MMA(0, 0, At, B0); PG8_MMA(0, 1, At, B1); PG8_BAR; PG8_SCHED;
;             PG8_LDA(At, 0, 1); PG8_STAGE(PG8_SB(0, 0), b2, voffB); PG8_STAGE(PG8_SB(0, 1), b2 + hstepB, voffB); PG8_STAGE(PG8_SA(0, 0), a2, voffA);
;             PG8_WAIT_V(8); PG8_WAIT_L(0); PG8_BAR; PG8_MMA(1, 0, At, B0); PG8_MMA(1, 1, At, B1); PG8_BAR; PG8_SCHED;
.LBB0_446:
	s_add_i32 s2, s33, 2
	s_add_u32 s3, s0, 0x80
	s_addc_u32 s36, s1, 0
	s_add_i32 s50, 0, 0x10000
	s_cmp_eq_u32 s18, s33
	s_cselect_b32 s37, s31, s36
	s_cselect_b32 s36, s30, s3
	v_add_u32_e32 v0, s50, v238
	s_cselect_b32 s49, s27, s29
	s_cselect_b32 s48, s26, s16
	s_add_i32 s3, 0, 0x14000
	s_waitcnt lgkmcnt(0)
	ds_read_b128 v[130:133], v0
	ds_read_b128 v[134:137], v0 offset:1024
	ds_read_b128 v[138:141], v0 offset:2048
	ds_read_b128 v[142:145], v0 offset:3072
	v_add_u32_e32 v0, s3, v238
	ds_read_b128 v[146:149], v0
	ds_read_b128 v[150:153], v0 offset:1024
	ds_read_b128 v[154:157], v0 offset:2048
	ds_read_b128 v[158:161], v0 offset:3072
	v_lshl_add_u64 v[194:195], s[0:1], 0, v[214:215]
	s_add_i32 m0, s13, 0xc000
	ds_read_b128 v[162:165], v245
	ds_read_b128 v[166:169], v245 offset:1024
	ds_read_b128 v[170:173], v245 offset:2048
	ds_read_b128 v[174:177], v245 offset:3072
	ds_read_b128 v[178:181], v245 offset:4096
	ds_read_b128 v[182:185], v245 offset:5120
	ds_read_b128 v[186:189], v245 offset:6144
	ds_read_b128 v[190:193], v245 offset:7168
	global_load_lds_dwordx4 v[194:195], off
	s_add_i32 m0, s13, 0xe000
	v_lshl_add_u64 v[194:195], s[0:1], 0, v[212:213]
	global_load_lds_dwordx4 v[194:195], off
	s_waitcnt vmcnt(8)
	s_waitcnt lgkmcnt(0)
	s_barrier
	s_setprio 1
	v_mfma_f32_16x16x32_bf16 v[126:129], v[130:133], v[162:165], v[126:129]
	v_mfma_f32_16x16x32_bf16 v[122:125], v[138:141], v[162:165], v[122:125]
	v_mfma_f32_16x16x32_bf16 v[110:113], v[130:133], v[170:173], v[110:113]
	v_mfma_f32_16x16x32_bf16 v[106:109], v[138:141], v[170:173], v[106:109]
	v_mfma_f32_16x16x32_bf16 v[94:97], v[130:133], v[178:181], v[94:97]
	v_mfma_f32_16x16x32_bf16 v[90:93], v[138:141], v[178:181], v[90:93]
	v_mfma_f32_16x16x32_bf16 v[78:81], v[130:133], v[186:189], v[78:81]
	v_mfma_f32_16x16x32_bf16 v[74:77], v[138:141], v[186:189], v[74:77]
	v_mfma_f32_16x16x32_bf16 v[126:129], v[134:137], v[166:169], v[126:129]
	v_mfma_f32_16x16x32_bf16 v[122:125], v[142:145], v[166:169], v[122:125]
	v_mfma_f32_16x16x32_bf16 v[110:113], v[134:137], v[174:177], v[110:113]
	v_mfma_f32_16x16x32_bf16 v[106:109], v[142:145], v[174:177], v[106:109]
	v_mfma_f32_16x16x32_bf16 v[94:97], v[134:137], v[182:185], v[94:97]
	v_mfma_f32_16x16x32_bf16 v[90:93], v[142:145], v[182:185], v[90:93]
	v_mfma_f32_16x16x32_bf16 v[78:81], v[134:137], v[190:193], v[78:81]
	v_mfma_f32_16x16x32_bf16 v[74:77], v[142:145], v[190:193], v[74:77]
	v_mfma_f32_16x16x32_bf16 v[118:121], v[146:149], v[162:165], v[118:121]
	v_mfma_f32_16x16x32_bf16 v[114:117], v[154:157], v[162:165], v[114:117]
	v_mfma_f32_16x16x32_bf16 v[102:105], v[146:149], v[170:173], v[102:105]
	v_mfma_f32_16x16x32_bf16 v[98:101], v[154:157], v[170:173], v[98:101]
	v_mfma_f32_16x16x32_bf16 v[86:89], v[146:149], v[178:181], v[86:89]
	v_mfma_f32_16x16x32_bf16 v[82:85], v[154:157], v[178:181], v[82:85]
	v_mfma_f32_16x16x32_bf16 v[70:73], v[146:149], v[186:189], v[70:73]
	v_mfma_f32_16x16x32_bf16 v[66:69], v[154:157], v[186:189], v[66:69]
	v_mfma_f32_16x16x32_bf16 v[118:121], v[150:153], v[166:169], v[118:121]
	v_mfma_f32_16x16x32_bf16 v[114:117], v[158:161], v[166:169], v[114:117]
	v_mfma_f32_16x16x32_bf16 v[102:105], v[150:153], v[174:177], v[102:105]
	v_mfma_f32_16x16x32_bf16 v[98:101], v[158:161], v[174:177], v[98:101]
	v_mfma_f32_16x16x32_bf16 v[86:89], v[150:153], v[182:185], v[86:89]
	v_mfma_f32_16x16x32_bf16 v[82:85], v[158:161], v[182:185], v[82:85]
	v_mfma_f32_16x16x32_bf16 v[70:73], v[150:153], v[190:193], v[70:73]
	v_mfma_f32_16x16x32_bf16 v[66:69], v[158:161], v[190:193], v[66:69]
	s_setprio 0
	s_barrier
	s_add_i32 s33, s50, s12
	v_lshl_add_u64 v[194:195], s[48:49], 0, v[200:201]
	s_mov_b32 m0, s33
	ds_read_b128 v[162:165], v245 offset:16384
	ds_read_b128 v[166:169], v245 offset:17408
	ds_read_b128 v[170:173], v245 offset:18432
	ds_read_b128 v[174:177], v245 offset:19456
	ds_read_b128 v[178:181], v245 offset:20480
	ds_read_b128 v[182:185], v245 offset:21504
	ds_read_b128 v[186:189], v245 offset:22528
	ds_read_b128 v[190:193], v245 offset:23552
	global_load_lds_dwordx4 v[194:195], off
	s_add_i32 m0, s33, 0x2000
	v_lshl_add_u64 v[196:197], s[48:49], 0, v[204:205]
	s_add_u32 s48, s48, s9
	s_addc_u32 s49, s49, 0
	s_add_i32 s3, s3, s12
	global_load_lds_dwordx4 v[196:197], off
	v_lshl_add_u64 v[216:217], s[48:49], 0, v[200:201]
	s_mov_b32 m0, s3
	v_lshl_add_u64 v[218:219], s[48:49], 0, v[204:205]
	global_load_lds_dwordx4 v[216:217], off
	s_add_i32 m0, s3, 0x2000
	v_lshl_add_u64 v[220:221], s[36:37], 0, v[198:199]
	global_load_lds_dwordx4 v[218:219], off
	s_mov_b32 m0, s13
	v_lshl_add_u64 v[222:223], s[36:37], 0, v[202:203]
	global_load_lds_dwordx4 v[220:221], off
	s_mov_b32 m0, s72
	s_nop 0
	global_load_lds_dwordx4 v[222:223], off
	s_waitcnt vmcnt(8)
	s_waitcnt lgkmcnt(0)
	s_barrier
; #define PG8_STAGE(bufoff, gbase, voff) do { _Pragma("unroll") for (int _i = 0; _i < 2; ++_i) \
;         __builtin_amdgcn_global_load_lds((const unsigned*)((const char*)(gbase) + (voff)[_i]), (LAS unsigned*)(lds + (bufoff) + ldsw + _i * 8192), 16, 0, 0); } while (0)
; #define PG8_LDA(dst, b, h) do { _Pragma("unroll") for (int m = 0; m < 4; ++m) _Pragma("unroll") for (int k = 0; k < 2; ++k) dst[m][k] = *(const LAS bf16x8*)(lds + PG8_SA(b, h) + aoff + m * 2048 + k * 1024); } while (0)
; #define PG8_LDB(dst, b, h) do { _Pragma("unroll") for (int n = 0; n < 2; ++n) _Pragma("unroll") for (int k = 0; k < 2; ++k) dst[n][k] = *(const LAS bf16x8*)(lds + PG8_SB(b, h) + boff + n * 2048 + k * 1024); } while (0)
; #define PG8_MMA(ai, bj, At, Bt) do { __builtin_amdgcn_s_setprio(1); _Pragma("unroll") for (int m = 0; m < 4; ++m) _Pragma("unroll") for (int n = 0; n < 2; ++n) _Pragma("unroll") for (int k = 0; k < 2; ++k) \
;         acc[ai][bj][m][n] = __builtin_amdgcn_mfma_f32_16x16x32_bf16(Bt[n][k], At[m][k], acc[ai][bj][m][n], 0, 0, 0); __builtin_amdgcn_s_setprio(0); } while (0)
; #define PG8_WAIT_V(n) asm volatile("s_waitcnt vmcnt(" #n ")" ::: "memory")
; #define PG8_WAIT_L(n) asm volatile("s_waitcnt lgkmcnt(" #n ")" ::: "memory")
; #define PG8_BAR __builtin_amdgcn_s_barrier()
; #define PG8_SCHED __builtin_amdgcn_sched_barrier(0)
; template <class Epi>
; DI void gemm_phase(LAS unsigned char* lds, const Gemm g, const StaticOrder& S, const Epi& E) {
;     ...
;             PG8_WAIT_V(8); PG8_WAIT_L(0); PG8_BAR; PG8_MMA(1, 0, At, B0); PG8_MMA(1, 1, At, B1); PG8_BAR; PG8_SCHED;
;             PG8_LDB(B0, 1, 0); PG8_LDB(B1, 1, 1); PG8_SCHED; PG8_LDA(At, 1, 0); PG8_STAGE(PG8_SA(0, 1), a2 + hstepA, voffA);
;             PG8_WAIT_V(8); PG8_WAIT_L(0); PG8_BAR; PG8_MMA(0, 0, At, B0); PG8_MMA(0, 1, At, B1); PG8_BAR; PG8_SCHED;
	s_setprio 1
	v_mfma_f32_16x16x32_bf16 v[62:65], v[130:133], v[162:165], v[62:65]
	v_mfma_f32_16x16x32_bf16 v[58:61], v[138:141], v[162:165], v[58:61]
	v_mfma_f32_16x16x32_bf16 v[46:49], v[130:133], v[170:173], v[46:49]
	v_mfma_f32_16x16x32_bf16 v[42:45], v[138:141], v[170:173], v[42:45]
	v_mfma_f32_16x16x32_bf16 v[30:33], v[130:133], v[178:181], v[30:33]
	v_mfma_f32_16x16x32_bf16 v[26:29], v[138:141], v[178:181], v[26:29]
	v_mfma_f32_16x16x32_bf16 v[14:17], v[130:133], v[186:189], v[14:17]
	v_mfma_f32_16x16x32_bf16 v[10:13], v[138:141], v[186:189], v[10:13]
	v_mfma_f32_16x16x32_bf16 v[62:65], v[134:137], v[166:169], v[62:65]
	v_mfma_f32_16x16x32_bf16 v[58:61], v[142:145], v[166:169], v[58:61]
	v_mfma_f32_16x16x32_bf16 v[46:49], v[134:137], v[174:177], v[46:49]
	v_mfma_f32_16x16x32_bf16 v[42:45], v[142:145], v[174:177], v[42:45]
	v_mfma_f32_16x16x32_bf16 v[30:33], v[134:137], v[182:185], v[30:33]
	v_mfma_f32_16x16x32_bf16 v[26:29], v[142:145], v[182:185], v[26:29]
	v_mfma_f32_16x16x32_bf16 v[14:17], v[134:137], v[190:193], v[14:17]
	v_mfma_f32_16x16x32_bf16 v[10:13], v[142:145], v[190:193], v[10:13]
	v_mfma_f32_16x16x32_bf16 v[54:57], v[146:149], v[162:165], v[54:57]
	v_mfma_f32_16x16x32_bf16 v[50:53], v[154:157], v[162:165], v[50:53]
	v_mfma_f32_16x16x32_bf16 v[38:41], v[146:149], v[170:173], v[38:41]
	v_mfma_f32_16x16x32_bf16 v[34:37], v[154:157], v[170:173], v[34:37]
	v_mfma_f32_16x16x32_bf16 v[22:25], v[146:149], v[178:181], v[22:25]
	v_mfma_f32_16x16x32_bf16 v[18:21], v[154:157], v[178:181], v[18:21]
	v_mfma_f32_16x16x32_bf16 v[6:9], v[146:149], v[186:189], v[6:9]
	v_mfma_f32_16x16x32_bf16 v[2:5], v[154:157], v[186:189], v[2:5]
	v_mfma_f32_16x16x32_bf16 v[54:57], v[150:153], v[166:169], v[54:57]
	v_mfma_f32_16x16x32_bf16 v[50:53], v[158:161], v[166:169], v[50:53]
	v_mfma_f32_16x16x32_bf16 v[38:41], v[150:153], v[174:177], v[38:41]
	v_mfma_f32_16x16x32_bf16 v[34:37], v[158:161], v[174:177], v[34:37]
	v_mfma_f32_16x16x32_bf16 v[22:25], v[150:153], v[182:185], v[22:25]
	v_mfma_f32_16x16x32_bf16 v[18:21], v[158:161], v[182:185], v[18:21]
	v_mfma_f32_16x16x32_bf16 v[6:9], v[150:153], v[190:193], v[6:9]
	v_mfma_f32_16x16x32_bf16 v[2:5], v[158:161], v[190:193], v[2:5]
	s_setprio 0
	s_barrier
	s_add_i32 s3, 0, 0x18000
	v_add_u32_e32 v0, s3, v238
	s_add_i32 s33, 0, 0x1c000
	ds_read_b128 v[130:133], v0
	ds_read_b128 v[134:137], v0 offset:1024
	ds_read_b128 v[138:141], v0 offset:2048
	ds_read_b128 v[142:145], v0 offset:3072
	v_add_u32_e32 v0, s33, v238
	ds_read_b128 v[146:149], v0
	ds_read_b128 v[150:153], v0 offset:1024
	ds_read_b128 v[154:157], v0 offset:2048
	ds_read_b128 v[158:161], v0 offset:3072
	s_add_u32 s36, s36, s56
	s_addc_u32 s37, s37, 0
	s_mov_b32 m0, s73
	v_lshl_add_u64 v[224:225], s[36:37], 0, v[198:199]
	ds_read_b128 v[162:165], v245 offset:32768
	ds_read_b128 v[166:169], v245 offset:33792
	ds_read_b128 v[170:173], v245 offset:34816
	ds_read_b128 v[174:177], v245 offset:35840
	ds_read_b128 v[178:181], v245 offset:36864
	ds_read_b128 v[182:185], v245 offset:37888
	ds_read_b128 v[186:189], v245 offset:38912
	ds_read_b128 v[190:193], v245 offset:39936
	global_load_lds_dwordx4 v[224:225], off
	s_mov_b32 m0, s74
	v_lshl_add_u64 v[224:225], s[36:37], 0, v[202:203]
	global_load_lds_dwordx4 v[224:225], off
	s_waitcnt vmcnt(8)
	s_waitcnt lgkmcnt(0)
	s_barrier
	s_setprio 1
	v_mfma_f32_16x16x32_bf16 v[126:129], v[130:133], v[162:165], v[126:129]
	v_mfma_f32_16x16x32_bf16 v[122:125], v[138:141], v[162:165], v[122:125]
	v_mfma_f32_16x16x32_bf16 v[110:113], v[130:133], v[170:173], v[110:113]
	v_mfma_f32_16x16x32_bf16 v[106:109], v[138:141], v[170:173], v[106:109]
	v_mfma_f32_16x16x32_bf16 v[94:97], v[130:133], v[178:181], v[94:97]
	v_mfma_f32_16x16x32_bf16 v[90:93], v[138:141], v[178:181], v[90:93]
	v_mfma_f32_16x16x32_bf16 v[78:81], v[130:133], v[186:189], v[78:81]
	v_mfma_f32_16x16x32_bf16 v[74:77], v[138:141], v[186:189], v[74:77]
	v_mfma_f32_16x16x32_bf16 v[126:129], v[134:137], v[166:169], v[126:129]
	v_mfma_f32_16x16x32_bf16 v[122:125], v[142:145], v[166:169], v[122:125]
	v_mfma_f32_16x16x32_bf16 v[110:113], v[134:137], v[174:177], v[110:113]
	v_mfma_f32_16x16x32_bf16 v[106:109], v[142:145], v[174:177], v[106:109]
	v_mfma_f32_16x16x32_bf16 v[94:97], v[134:137], v[182:185], v[94:97]
	v_mfma_f32_16x16x32_bf16 v[90:93], v[142:145], v[182:185], v[90:93]
	v_mfma_f32_16x16x32_bf16 v[78:81], v[134:137], v[190:193], v[78:81]
	v_mfma_f32_16x16x32_bf16 v[74:77], v[142:145], v[190:193], v[74:77]
	v_mfma_f32_16x16x32_bf16 v[118:121], v[146:149], v[162:165], v[118:121]
	v_mfma_f32_16x16x32_bf16 v[114:117], v[154:157], v[162:165], v[114:117]
	v_mfma_f32_16x16x32_bf16 v[102:105], v[146:149], v[170:173], v[102:105]
	v_mfma_f32_16x16x32_bf16 v[98:101], v[154:157], v[170:173], v[98:101]
	v_mfma_f32_16x16x32_bf16 v[86:89], v[146:149], v[178:181], v[86:89]
	v_mfma_f32_16x16x32_bf16 v[82:85], v[154:157], v[178:181], v[82:85]
	v_mfma_f32_16x16x32_bf16 v[70:73], v[146:149], v[186:189], v[70:73]
	v_mfma_f32_16x16x32_bf16 v[66:69], v[154:157], v[186:189], v[66:69]
	v_mfma_f32_16x16x32_bf16 v[118:121], v[150:153], v[166:169], v[118:121]
	v_mfma_f32_16x16x32_bf16 v[114:117], v[158:161], v[166:169], v[114:117]
	v_mfma_f32_16x16x32_bf16 v[102:105], v[150:153], v[174:177], v[102:105]
	v_mfma_f32_16x16x32_bf16 v[98:101], v[158:161], v[174:177], v[98:101]
	v_mfma_f32_16x16x32_bf16 v[86:89], v[150:153], v[182:185], v[86:89]
	v_mfma_f32_16x16x32_bf16 v[82:85], v[158:161], v[182:185], v[82:85]
	v_mfma_f32_16x16x32_bf16 v[70:73], v[150:153], v[190:193], v[70:73]
	v_mfma_f32_16x16x32_bf16 v[66:69], v[158:161], v[190:193], v[66:69]
	s_setprio 0
	s_barrier
; #define PG8_STAGE(bufoff, gbase, voff) do { _Pragma("unroll") for (int _i = 0; _i < 2; ++_i) \
;         __builtin_amdgcn_global_load_lds((const unsigned*)((const char*)(gbase) + (voff)[_i]), (LAS unsigned*)(lds + (bufoff) + ldsw + _i * 8192), 16, 0, 0); } while (0)
; #define PG8_LDA(dst, b, h) do { _Pragma("unroll") for (int m = 0; m < 4; ++m) _Pragma("unroll") for (int k = 0; k < 2; ++k) dst[m][k] = *(const LAS bf16x8*)(lds + PG8_SA(b, h) + aoff + m * 2048 + k * 1024); } while (0)
; #define PG8_MMA(ai, bj, At, Bt) do { __builtin_amdgcn_s_setprio(1); _Pragma("unroll") for (int m = 0; m < 4; ++m) _Pragma("unroll") for (int n = 0; n < 2; ++n) _Pragma("unroll") for (int k = 0; k < 2; ++k) \
;         acc[ai][bj][m][n] = __builtin_amdgcn_mfma_f32_16x16x32_bf16(Bt[n][k], At[m][k], acc[ai][bj][m][n], 0, 0, 0); __builtin_amdgcn_s_setprio(0); } while (0)
; #define PG8_WAIT_V(n) asm volatile("s_waitcnt vmcnt(" #n ")" ::: "memory")
; #define PG8_WAIT_L(n) asm volatile("s_waitcnt lgkmcnt(" #n ")" ::: "memory")
; #define PG8_BAR __builtin_amdgcn_s_barrier()
; #define PG8_SCHED __builtin_amdgcn_sched_barrier(0)
; template <class Epi>
; DI void gemm_phase(LAS unsigned char* lds, const Gemm g, const StaticOrder& S, const Epi& E) {
;     ...
;             PG8_LDA(At, 1, 1); PG8_STAGE(PG8_SB(1, 0), b3, voffB); PG8_STAGE(PG8_SB(1, 1), b3 + hstepB, voffB); PG8_STAGE(PG8_SA(1, 0), a3, voffA);
;             PG8_WAIT_V(8); PG8_WAIT_L(0); PG8_BAR; PG8_MMA(1, 0, At, B0); PG8_MMA(1, 1, At, B1); PG8_BAR; PG8_SCHED;
;         }
;         if (wr == 0) PG8_BAR;
	s_add_i32 s3, s3, s12
	v_lshl_add_u64 v[194:195], v[194:195], 0, s[34:35]
	s_mov_b32 m0, s3
	ds_read_b128 v[162:165], v245 offset:49152
	ds_read_b128 v[166:169], v245 offset:50176
	ds_read_b128 v[170:173], v245 offset:51200
	ds_read_b128 v[174:177], v245 offset:52224
	ds_read_b128 v[178:181], v245 offset:53248
	ds_read_b128 v[182:185], v245 offset:54272
	ds_read_b128 v[186:189], v245 offset:55296
	ds_read_b128 v[190:193], v245 offset:56320
	global_load_lds_dwordx4 v[194:195], off
	v_lshl_add_u64 v[194:195], v[196:197], 0, s[34:35]
	s_add_i32 m0, s3, 0x2000
	s_add_i32 s3, s33, s12
	global_load_lds_dwordx4 v[194:195], off
	s_mov_b32 m0, s3
	v_lshl_add_u64 v[194:195], v[216:217], 0, s[34:35]
	global_load_lds_dwordx4 v[194:195], off
	s_add_i32 m0, s3, 0x2000
	v_lshl_add_u64 v[194:195], v[218:219], 0, s[34:35]
	global_load_lds_dwordx4 v[194:195], off
	s_mov_b32 m0, s75
	v_lshl_add_u64 v[194:195], v[220:221], 0, s[34:35]
	global_load_lds_dwordx4 v[194:195], off
	s_mov_b32 m0, s54
	v_lshl_add_u64 v[194:195], v[222:223], 0, s[34:35]
	global_load_lds_dwordx4 v[194:195], off
	s_waitcnt vmcnt(8)
	s_waitcnt lgkmcnt(0)
	s_barrier
	s_setprio 1
	v_mfma_f32_16x16x32_bf16 v[62:65], v[130:133], v[162:165], v[62:65]
	v_mfma_f32_16x16x32_bf16 v[58:61], v[138:141], v[162:165], v[58:61]
	v_mfma_f32_16x16x32_bf16 v[46:49], v[130:133], v[170:173], v[46:49]
	v_mfma_f32_16x16x32_bf16 v[42:45], v[138:141], v[170:173], v[42:45]
	v_mfma_f32_16x16x32_bf16 v[30:33], v[130:133], v[178:181], v[30:33]
	v_mfma_f32_16x16x32_bf16 v[26:29], v[138:141], v[178:181], v[26:29]
	v_mfma_f32_16x16x32_bf16 v[14:17], v[130:133], v[186:189], v[14:17]
	v_mfma_f32_16x16x32_bf16 v[10:13], v[138:141], v[186:189], v[10:13]
	v_mfma_f32_16x16x32_bf16 v[62:65], v[134:137], v[166:169], v[62:65]
	v_mfma_f32_16x16x32_bf16 v[58:61], v[142:145], v[166:169], v[58:61]
	v_mfma_f32_16x16x32_bf16 v[46:49], v[134:137], v[174:177], v[46:49]
	v_mfma_f32_16x16x32_bf16 v[42:45], v[142:145], v[174:177], v[42:45]
	v_mfma_f32_16x16x32_bf16 v[30:33], v[134:137], v[182:185], v[30:33]
	v_mfma_f32_16x16x32_bf16 v[26:29], v[142:145], v[182:185], v[26:29]
	v_mfma_f32_16x16x32_bf16 v[14:17], v[134:137], v[190:193], v[14:17]
	v_mfma_f32_16x16x32_bf16 v[10:13], v[142:145], v[190:193], v[10:13]
	v_mfma_f32_16x16x32_bf16 v[54:57], v[146:149], v[162:165], v[54:57]
	v_mfma_f32_16x16x32_bf16 v[50:53], v[154:157], v[162:165], v[50:53]
	v_mfma_f32_16x16x32_bf16 v[38:41], v[146:149], v[170:173], v[38:41]
	v_mfma_f32_16x16x32_bf16 v[34:37], v[154:157], v[170:173], v[34:37]
	v_mfma_f32_16x16x32_bf16 v[22:25], v[146:149], v[178:181], v[22:25]
	v_mfma_f32_16x16x32_bf16 v[18:21], v[154:157], v[178:181], v[18:21]
	v_mfma_f32_16x16x32_bf16 v[6:9], v[146:149], v[186:189], v[6:9]
	v_mfma_f32_16x16x32_bf16 v[2:5], v[154:157], v[186:189], v[2:5]
	v_mfma_f32_16x16x32_bf16 v[54:57], v[150:153], v[166:169], v[54:57]
	v_mfma_f32_16x16x32_bf16 v[50:53], v[158:161], v[166:169], v[50:53]
	v_mfma_f32_16x16x32_bf16 v[38:41], v[150:153], v[174:177], v[38:41]
	v_mfma_f32_16x16x32_bf16 v[34:37], v[158:161], v[174:177], v[34:37]
	v_mfma_f32_16x16x32_bf16 v[22:25], v[150:153], v[182:185], v[22:25]
	v_mfma_f32_16x16x32_bf16 v[18:21], v[158:161], v[182:185], v[18:21]
	v_mfma_f32_16x16x32_bf16 v[6:9], v[150:153], v[190:193], v[6:9]
	v_mfma_f32_16x16x32_bf16 v[2:5], v[158:161], v[190:193], v[2:5]
	s_setprio 0
	s_barrier
	s_add_u32 s16, s16, 0x100
	s_addc_u32 s29, s29, 0
	s_add_u32 s0, s0, 0x100
	s_addc_u32 s1, s1, 0
	s_cmp_ge_u32 s2, s5
	s_mov_b32 s33, s2
	s_cbranch_scc0 .LBB0_446
	s_and_b64 vcc, exec, s[70:71]
	s_cbranch_vccz .LBB0_450
	s_barrier
	s_cmp_lt_i32 s24, 2
	s_mov_b64 s[0:1], -1
	s_cbranch_scc0 .LBB0_451
